# k20 + 4 more MoBA gating xor-32 exchanges via v_permlane32_swap
# baseline (speedup 1.0000x reference)
.LBB0_1498:
	s_or_b64 exec, exec, s[0:1]
	v_readfirstlane_b32 s40, v0
	s_cmpk_gt_u32 s40, 0x7ff
	s_mov_b64 s[0:1], -1
	s_cbranch_scc1 .LBB0_1493
	s_xor_b32 s40, s40, 0x400
	v_mov_b32_e32 v188, v240
	s_cmpk_gt_u32 s40, 0x3ff
	v_ashrrev_i32_e32 v196, 5, v188
	s_cbranch_scc0 .LBB0_1565
	s_not_b32 s0, s40
	s_bfe_u32 s42, s0, 0x60002
	v_ashrrev_i32_e32 v189, 5, v188
	s_and_b32 s43, s40, 3
	s_lshl_b32 s41, s42, 5
	s_waitcnt vmcnt(15)
	v_lshlrev_b32_e32 v146, 3, v189
	s_cmpk_gt_u32 s40, 0x5ff
	v_and_or_b32 v190, v188, 31, s41
	v_ashrrev_i32_e32 v147, 31, v146
	s_mov_b64 s[0:1], -1
	s_cbranch_scc0 .LBB0_1541
	s_add_i32 s0, s40, 0xfffffa00
	s_lshr_b32 s0, s0, 6
	s_and_b32 s0, s0, 0x3fffffc
	v_readlane_b32 s1, v255, 1
	s_add_i32 s0, s0, s1
	s_or_b32 s36, s0, s43
	s_lshl_b32 s0, s0, 9
	s_and_b32 s0, s0, 0x7800
	v_or_b32_e32 v184, s0, v190
	v_readlane_b32 s0, v255, 6
	v_lshlrev_b32_e32 v0, 9, v184
	v_readlane_b32 s1, v255, 7
	s_mov_b32 s19, s37
	v_readlane_b32 s2, v255, 10
	v_lshl_add_u64 v[2:3], s[0:1], 0, v[0:1]
	s_lshl_b32 s0, s36, 6
	s_and_b32 s0, s0, 0xc0
	s_lshl_b32 s18, s0, 1
	v_lshl_add_u64 v[2:3], v[2:3], 0, s[18:19]
	v_lshl_add_u64 v[2:3], v[146:147], 1, v[2:3]
	global_load_dwordx4 v[66:69], v[2:3], off
	global_load_dwordx4 v[70:73], v[2:3], off offset:32
	global_load_dwordx4 v[74:77], v[2:3], off offset:64
	global_load_dwordx4 v[78:81], v[2:3], off offset:96
	s_lshl_b64 s[0:1], s[36:37], 11
	s_add_u32 s0, s2, s0
	v_readlane_b32 s2, v255, 11
	s_addc_u32 s1, s2, s1
	s_cmp_lt_u32 s42, 8
	v_lshl_add_u64 v[2:3], v[146:147], 2, s[0:1]
	s_cselect_b64 s[0:1], -1, 0
	v_mov_b32_e32 v0, 0
	v_mov_b32_e32 v16, 0
	s_and_b64 vcc, exec, s[0:1]
	s_waitcnt vmcnt(3)
	v_lshlrev_b32_e32 v29, 16, v66
	v_lshlrev_b32_e32 v30, 16, v68
	v_and_b32_e32 v31, 0xffff0000, v66
	v_and_b32_e32 v32, 0xffff0000, v68
	v_lshlrev_b32_e32 v33, 16, v67
	v_lshlrev_b32_e32 v34, 16, v69
	v_and_b32_e32 v35, 0xffff0000, v67
	v_and_b32_e32 v36, 0xffff0000, v69
	s_waitcnt vmcnt(2)
	v_lshlrev_b32_e32 v21, 16, v70
	v_lshlrev_b32_e32 v22, 16, v72
	v_and_b32_e32 v23, 0xffff0000, v70
	v_and_b32_e32 v24, 0xffff0000, v72
	v_lshlrev_b32_e32 v25, 16, v71
	v_lshlrev_b32_e32 v26, 16, v73
	v_and_b32_e32 v27, 0xffff0000, v71
	v_and_b32_e32 v28, 0xffff0000, v73
	s_waitcnt vmcnt(1)
	v_lshlrev_b32_e32 v17, 16, v74
	v_lshlrev_b32_e32 v18, 16, v76
	v_and_b32_e32 v19, 0xffff0000, v74
	v_and_b32_e32 v20, 0xffff0000, v76
	v_lshlrev_b32_e32 v15, 16, v75
	v_lshlrev_b32_e32 v14, 16, v77
	v_and_b32_e32 v13, 0xffff0000, v75
	v_and_b32_e32 v12, 0xffff0000, v77
	s_waitcnt vmcnt(0)
	v_lshlrev_b32_e32 v11, 16, v78
	v_lshlrev_b32_e32 v10, 16, v80
	v_and_b32_e32 v9, 0xffff0000, v78
	v_and_b32_e32 v8, 0xffff0000, v80
	v_lshlrev_b32_e32 v7, 16, v79
	v_lshlrev_b32_e32 v6, 16, v81
	v_and_b32_e32 v5, 0xffff0000, v79
	v_and_b32_e32 v4, 0xffff0000, v81
	v_lshlrev_b32_e32 v62, 4, v188
	v_lshrrev_b32_e32 v53, 5, v188
	v_lshlrev_b32_e32 v53, 5, v53
	v_sub_u32_e32 v62, v62, v53
	v_mov_b32_e32 v63, 0
	v_lshl_add_u64 v[64:65], v[2:3], 0, v[62:63]
	global_load_dwordx4 v[54:57], v[64:65], off
	global_load_dwordx4 v[58:61], v[64:65], off offset:1024
	v_readlane_b32 s2, v253, 16
	s_lshl_b32 s2, s2, 14
	s_nop 1
	v_lshl_add_u32 v62, v188, 4, s2
	v_add_u32_e32 v52, s2, v53
	s_waitcnt vmcnt(0)
	ds_write_b128 v62, v[54:57]
	ds_write_b128 v62, v[58:61] offset:1024
	s_waitcnt lgkmcnt(0)
	s_cbranch_vccnz .LBB0_1503
	ds_read_b128 v[38:41], v52 offset:16
	ds_read_b128 v[42:45], v52
	v_xor_b32_e32 v37, 32, v235
	s_waitcnt lgkmcnt(0)
	v_fma_f32 v16, v42, v29, 0
	v_fmac_f32_e32 v16, v38, v30
	v_fmac_f32_e32 v16, v43, v31
	v_fmac_f32_e32 v16, v39, v32
	v_fmac_f32_e32 v16, v44, v33
	v_fmac_f32_e32 v16, v40, v34
	v_fmac_f32_e32 v16, v45, v35
	v_fmac_f32_e32 v16, v41, v36
	ds_read_b128 v[38:41], v52 offset:80
	ds_read_b128 v[42:45], v52 offset:64
	s_waitcnt lgkmcnt(0)
	v_fmac_f32_e32 v16, v42, v21
	v_fmac_f32_e32 v16, v38, v22
	v_fmac_f32_e32 v16, v43, v23
	v_fmac_f32_e32 v16, v39, v24
	v_fmac_f32_e32 v16, v44, v25
	v_fmac_f32_e32 v16, v40, v26
	v_fmac_f32_e32 v16, v45, v27
	v_fmac_f32_e32 v16, v41, v28
	ds_read_b128 v[38:41], v52 offset:144
	ds_read_b128 v[42:45], v52 offset:128
	s_waitcnt lgkmcnt(0)
	v_fmac_f32_e32 v16, v42, v17
	v_fmac_f32_e32 v16, v38, v18
	v_fmac_f32_e32 v16, v43, v19
	v_fmac_f32_e32 v16, v39, v20
	v_mov_b32_e32 v38, v40
	v_mov_b32_e32 v39, v44
	v_pk_mul_f32 v[38:39], v[38:39], v[14:15]
	v_mov_b32_e32 v44, v41
	v_add_f32_e32 v16, v39, v16
	v_add_f32_e32 v16, v38, v16
	v_pk_mul_f32 v[38:39], v[44:45], v[12:13]
	s_nop 0
	v_add_f32_e32 v16, v39, v16
	v_add_f32_e32 v16, v38, v16
	ds_read_b128 v[38:41], v52 offset:208
	ds_read_b128 v[42:45], v52 offset:192
	s_waitcnt lgkmcnt(1)
	v_mov_b32_e32 v46, v38
	s_waitcnt lgkmcnt(0)
	v_mov_b32_e32 v47, v42
	v_pk_mul_f32 v[46:47], v[46:47], v[10:11]
	v_mov_b32_e32 v42, v39
	v_add_f32_e32 v16, v47, v16
	v_add_f32_e32 v16, v46, v16
	v_pk_mul_f32 v[38:39], v[42:43], v[8:9]
	s_nop 0
	v_add_f32_e32 v16, v39, v16
	v_add_f32_e32 v16, v38, v16
	v_mov_b32_e32 v38, v40
	v_mov_b32_e32 v39, v44
	v_pk_mul_f32 v[38:39], v[38:39], v[6:7]
	v_mov_b32_e32 v44, v41
	v_add_f32_e32 v16, v39, v16
	v_add_f32_e32 v16, v38, v16
	v_pk_mul_f32 v[38:39], v[44:45], v[4:5]
	s_nop 0
	v_add_f32_e32 v16, v39, v16
	v_add_f32_e32 v16, v38, v16
	v_and_b32_e32 v38, 64, v235
	v_add_u32_e32 v38, 64, v38
	v_cmp_lt_i32_e32 vcc, v37, v38
	s_nop 1
	v_cndmask_b32_e32 v37, v235, v37, vcc
	v_lshlrev_b32_e32 v37, 2, v37
	v_mov_b32_e32 v37, v16
	s_nop 1
	v_permlane32_swap_b32 v37, v16
	s_waitcnt lgkmcnt(0)
	v_add_f32_e32 v16, v16, v37
.LBB0_1503:
	s_cmp_gt_u32 s42, 15
	s_cselect_b64 s[8:9], -1, 0
	s_cmp_lt_u32 s42, 16
	s_cbranch_scc1 .LBB0_1505
	ds_read_b128 v[38:41], v52 offset:272
	ds_read_b128 v[42:45], v52 offset:256
	v_xor_b32_e32 v37, 32, v235
	s_waitcnt lgkmcnt(0)
	v_fma_f32 v0, v42, v29, 0
	v_fmac_f32_e32 v0, v38, v30
	v_fmac_f32_e32 v0, v43, v31
	v_fmac_f32_e32 v0, v39, v32
	v_fmac_f32_e32 v0, v44, v33
	v_fmac_f32_e32 v0, v40, v34
	v_fmac_f32_e32 v0, v45, v35
	v_fmac_f32_e32 v0, v41, v36
	ds_read_b128 v[38:41], v52 offset:336
	ds_read_b128 v[42:45], v52 offset:320
	s_waitcnt lgkmcnt(0)
	v_fmac_f32_e32 v0, v42, v21
	v_fmac_f32_e32 v0, v38, v22
	v_fmac_f32_e32 v0, v43, v23
	v_fmac_f32_e32 v0, v39, v24
	v_fmac_f32_e32 v0, v44, v25
	v_fmac_f32_e32 v0, v40, v26
	v_fmac_f32_e32 v0, v45, v27
	v_fmac_f32_e32 v0, v41, v28
	ds_read_b128 v[38:41], v52 offset:400
	ds_read_b128 v[42:45], v52 offset:384
	s_waitcnt lgkmcnt(0)
	v_fmac_f32_e32 v0, v42, v17
	v_fmac_f32_e32 v0, v38, v18
	v_fmac_f32_e32 v0, v43, v19
	v_fmac_f32_e32 v0, v39, v20
	v_mov_b32_e32 v38, v40
	v_mov_b32_e32 v39, v44
	v_pk_mul_f32 v[38:39], v[38:39], v[14:15]
	v_mov_b32_e32 v44, v41
	v_add_f32_e32 v0, v39, v0
	v_add_f32_e32 v0, v38, v0
	v_pk_mul_f32 v[38:39], v[44:45], v[12:13]
	s_nop 0
	v_add_f32_e32 v0, v39, v0
	v_add_f32_e32 v0, v38, v0
	ds_read_b128 v[38:41], v52 offset:464
	ds_read_b128 v[42:45], v52 offset:448
	s_waitcnt lgkmcnt(1)
	v_mov_b32_e32 v46, v38
	s_waitcnt lgkmcnt(0)
	v_mov_b32_e32 v47, v42
	v_pk_mul_f32 v[46:47], v[46:47], v[10:11]
	v_mov_b32_e32 v42, v39
	v_add_f32_e32 v0, v47, v0
	v_add_f32_e32 v0, v46, v0
	v_pk_mul_f32 v[38:39], v[42:43], v[8:9]
	s_nop 0
	v_add_f32_e32 v0, v39, v0
	v_add_f32_e32 v0, v38, v0
	v_mov_b32_e32 v38, v40
	v_mov_b32_e32 v39, v44
	v_pk_mul_f32 v[38:39], v[38:39], v[6:7]
	v_mov_b32_e32 v44, v41
	v_add_f32_e32 v0, v39, v0
	v_add_f32_e32 v0, v38, v0
	v_pk_mul_f32 v[38:39], v[44:45], v[4:5]
	s_nop 0
	v_add_f32_e32 v0, v39, v0
	v_add_f32_e32 v0, v38, v0
	v_and_b32_e32 v38, 64, v235
	v_add_u32_e32 v38, 64, v38
	v_cmp_lt_i32_e32 vcc, v37, v38
	s_nop 1
	v_cndmask_b32_e32 v37, v235, v37, vcc
	v_lshlrev_b32_e32 v37, 2, v37
	v_mov_b32_e32 v37, v0
	s_nop 1
	v_permlane32_swap_b32 v37, v0
	s_waitcnt lgkmcnt(0)
	v_add_f32_e32 v0, v0, v37

.LBB0_1507:
	s_cmp_gt_u32 s42, 31
	s_cselect_b64 s[22:23], -1, 0
	s_cmp_lt_u32 s42, 32
	s_cbranch_scc1 .LBB0_1509
	ds_read_b128 v[40:43], v52 offset:784
	ds_read_b128 v[44:47], v52 offset:768
	v_xor_b32_e32 v39, 32, v235
	s_waitcnt lgkmcnt(0)
	v_fma_f32 v37, v44, v29, 0
	v_fmac_f32_e32 v37, v40, v30
	v_fmac_f32_e32 v37, v45, v31
	v_fmac_f32_e32 v37, v41, v32
	v_fmac_f32_e32 v37, v46, v33
	v_fmac_f32_e32 v37, v42, v34
	v_fmac_f32_e32 v37, v47, v35
	v_fmac_f32_e32 v37, v43, v36
	ds_read_b128 v[40:43], v52 offset:848
	ds_read_b128 v[44:47], v52 offset:832
	s_waitcnt lgkmcnt(0)
	v_fmac_f32_e32 v37, v44, v21
	v_fmac_f32_e32 v37, v40, v22
	v_fmac_f32_e32 v37, v45, v23
	v_fmac_f32_e32 v37, v41, v24
	v_fmac_f32_e32 v37, v46, v25
	v_fmac_f32_e32 v37, v42, v26
	v_fmac_f32_e32 v37, v47, v27
	v_fmac_f32_e32 v37, v43, v28
	ds_read_b128 v[40:43], v52 offset:912
	ds_read_b128 v[44:47], v52 offset:896
	s_waitcnt lgkmcnt(0)
	v_fmac_f32_e32 v37, v44, v17
	v_fmac_f32_e32 v37, v40, v18
	v_fmac_f32_e32 v37, v45, v19
	v_fmac_f32_e32 v37, v41, v20
	v_mov_b32_e32 v40, v42
	v_mov_b32_e32 v41, v46
	v_pk_mul_f32 v[40:41], v[40:41], v[14:15]
	v_mov_b32_e32 v46, v43
	v_add_f32_e32 v37, v41, v37
	v_add_f32_e32 v37, v40, v37
	v_pk_mul_f32 v[40:41], v[46:47], v[12:13]
	s_nop 0
	v_add_f32_e32 v37, v41, v37
	v_add_f32_e32 v37, v40, v37
	ds_read_b128 v[40:43], v52 offset:976
	ds_read_b128 v[44:47], v52 offset:960
	s_waitcnt lgkmcnt(1)
	v_mov_b32_e32 v48, v40
	s_waitcnt lgkmcnt(0)
	v_mov_b32_e32 v49, v44
	v_pk_mul_f32 v[48:49], v[48:49], v[10:11]
	v_mov_b32_e32 v44, v41
	v_add_f32_e32 v37, v49, v37
	v_add_f32_e32 v37, v48, v37
	v_pk_mul_f32 v[40:41], v[44:45], v[8:9]
	s_nop 0
	v_add_f32_e32 v37, v41, v37
	v_add_f32_e32 v37, v40, v37
	v_mov_b32_e32 v40, v42
	v_mov_b32_e32 v41, v46
	v_pk_mul_f32 v[40:41], v[40:41], v[6:7]
	v_mov_b32_e32 v46, v43
	v_add_f32_e32 v37, v41, v37
	v_add_f32_e32 v37, v40, v37
	v_pk_mul_f32 v[40:41], v[46:47], v[4:5]
	s_nop 0
	v_add_f32_e32 v37, v41, v37
	v_add_f32_e32 v37, v40, v37
	v_and_b32_e32 v40, 64, v235
	v_add_u32_e32 v40, 64, v40
	v_cmp_lt_i32_e32 vcc, v39, v40
	s_nop 1
	v_cndmask_b32_e32 v39, v235, v39, vcc
	v_lshlrev_b32_e32 v39, 2, v39
	v_mov_b32_e32 v39, v37
	s_nop 1
	v_permlane32_swap_b32 v39, v37
	s_waitcnt lgkmcnt(0)
	v_add_f32_e32 v37, v37, v39

.LBB0_1511:
	s_cmp_gt_u32 s42, 47
	s_cselect_b64 s[26:27], -1, 0
	s_cmp_lt_u32 s42, 48
	s_cbranch_scc1 .LBB0_1513
	ds_read_b128 v[42:45], v52 offset:1296
	ds_read_b128 v[46:49], v52 offset:1280
	v_xor_b32_e32 v41, 32, v235
	s_waitcnt lgkmcnt(0)
	v_fma_f32 v39, v46, v29, 0
	v_fmac_f32_e32 v39, v42, v30
	v_fmac_f32_e32 v39, v47, v31
	v_fmac_f32_e32 v39, v43, v32
	v_fmac_f32_e32 v39, v48, v33
	v_fmac_f32_e32 v39, v44, v34
	v_fmac_f32_e32 v39, v49, v35
	v_fmac_f32_e32 v39, v45, v36
	ds_read_b128 v[42:45], v52 offset:1360
	ds_read_b128 v[46:49], v52 offset:1344
	s_waitcnt lgkmcnt(0)
	v_fmac_f32_e32 v39, v46, v21
	v_fmac_f32_e32 v39, v42, v22
	v_fmac_f32_e32 v39, v47, v23
	v_fmac_f32_e32 v39, v43, v24
	v_fmac_f32_e32 v39, v48, v25
	v_fmac_f32_e32 v39, v44, v26
	v_fmac_f32_e32 v39, v49, v27
	v_fmac_f32_e32 v39, v45, v28
	ds_read_b128 v[42:45], v52 offset:1424
	ds_read_b128 v[46:49], v52 offset:1408
	s_waitcnt lgkmcnt(0)
	v_fmac_f32_e32 v39, v46, v17
	v_fmac_f32_e32 v39, v42, v18
	v_fmac_f32_e32 v39, v47, v19
	v_fmac_f32_e32 v39, v43, v20
	v_mov_b32_e32 v42, v44
	v_mov_b32_e32 v43, v48
	v_pk_mul_f32 v[42:43], v[42:43], v[14:15]
	v_mov_b32_e32 v48, v45
	v_add_f32_e32 v39, v43, v39
	v_add_f32_e32 v39, v42, v39
	v_pk_mul_f32 v[42:43], v[48:49], v[12:13]
	s_nop 0
	v_add_f32_e32 v39, v43, v39
	v_add_f32_e32 v39, v42, v39
	ds_read_b128 v[42:45], v52 offset:1488
	ds_read_b128 v[46:49], v52 offset:1472
	s_waitcnt lgkmcnt(1)
	v_mov_b32_e32 v50, v42
	s_waitcnt lgkmcnt(0)
	v_mov_b32_e32 v51, v46
	v_pk_mul_f32 v[50:51], v[50:51], v[10:11]
	v_mov_b32_e32 v46, v43
	v_add_f32_e32 v39, v51, v39
	v_add_f32_e32 v39, v50, v39
	v_pk_mul_f32 v[42:43], v[46:47], v[8:9]
	s_nop 0
	v_add_f32_e32 v39, v43, v39
	v_add_f32_e32 v39, v42, v39
	v_mov_b32_e32 v42, v44
	v_mov_b32_e32 v43, v48
	v_pk_mul_f32 v[42:43], v[42:43], v[6:7]
	v_mov_b32_e32 v48, v45
	v_add_f32_e32 v39, v43, v39
	v_add_f32_e32 v39, v42, v39
	v_pk_mul_f32 v[42:43], v[48:49], v[4:5]
	s_nop 0
	v_add_f32_e32 v39, v43, v39
	v_add_f32_e32 v39, v42, v39
	v_and_b32_e32 v42, 64, v235
	v_add_u32_e32 v42, 64, v42
	v_cmp_lt_i32_e32 vcc, v41, v42
	s_nop 1
	v_cndmask_b32_e32 v41, v235, v41, vcc
	v_lshlrev_b32_e32 v41, 2, v41
	v_mov_b32_e32 v41, v39
	s_nop 1
	v_permlane32_swap_b32 v41, v39
	s_waitcnt lgkmcnt(0)
	v_add_f32_e32 v39, v39, v41
